# nsa top-k: threshold bit search starts at bit 37 (keys are below 2^38, so the two skipped trials could never succeed)
# baseline (speedup 1.0000x reference)
.LBB0_1456:
	v_lshl_add_u32 v0, s73, 9, v99
	s_waitcnt vmcnt(2)
	ds_read2st64_b32 v[56:57], v0 offset1:1
	v_mov_b32_e32 v59, v1
	s_mov_b64 s[68:69], 0
	s_mov_b64 s[70:71], 37
	s_waitcnt lgkmcnt(0)
	v_mov_b32_e32 v0, v56
	v_mov_b32_e32 v58, v57
	v_lshlrev_b64 v[56:57], 7, v[0:1]
	v_lshlrev_b64 v[58:59], 7, v[58:59]
	v_cndmask_b32_e64 v57, v57, 39, s[14:15]
	v_cndmask_b32_e64 v56, v56, v133, s[14:15]
	v_cndmask_b32_e64 v55, v58, v133, s[16:17]
	v_cndmask_b32_e64 v0, v59, 39, s[16:17]
	v_lshl_add_u64 v[56:57], v[56:57], 0, v[52:53]
	v_or_b32_e32 v55, v55, v54
	v_cndmask_b32_e64 v57, v57, 0, s[18:19]
	v_cndmask_b32_e64 v56, v56, 0, s[18:19]
	v_cndmask_b32_e64 v59, v0, 0, s[20:21]
	v_cndmask_b32_e64 v58, v55, 0, s[20:21]
	v_not_b32_e32 v0, 39
